# final candidate with hazard-safe scan wait counts (vmcnt 19-k valid also on a unit's last chunk step)
# speedup vs baseline: 1.0007x; 1.0007x over previous
.LBB0_487:
	s_andn2_b64 vcc, exec, s[20:21]
	s_waitcnt vmcnt(19)
	ds_write_b128 v193, v[2:5]
	s_waitcnt vmcnt(18)
	ds_write_b128 v194, v[6:9]
	s_waitcnt vmcnt(17)
	ds_write_b128 v195, v[10:13]
	s_waitcnt vmcnt(16)
	ds_write_b128 v196, v[14:17]
	s_waitcnt vmcnt(15)
	ds_write_b128 v197, v[18:21]
	s_waitcnt vmcnt(14)
	ds_write_b128 v198, v[22:25]
	s_waitcnt vmcnt(13)
	ds_write_b128 v199, v[26:29]
	s_waitcnt vmcnt(12)
	ds_write_b128 v200, v[30:33]
	s_waitcnt vmcnt(11)
	ds_write_b128 v201, v[34:37]
	s_waitcnt vmcnt(10)
	ds_write_b128 v202, v[38:41]
	s_waitcnt vmcnt(9)
	ds_write_b128 v203, v[42:45]
	s_waitcnt vmcnt(8)
	ds_write_b128 v204, v[46:49]
	s_waitcnt lgkmcnt(0)
	s_barrier
	s_cbranch_vccnz .LBB0_489
	s_ashr_i32 s19, s18, 31
	s_lshl_b64 s[20:21], s[18:19], 19
	v_lshl_add_u64 v[26:27], v[172:173], 0, s[20:21]
	v_add_co_u32_e32 v6, vcc, 0x2000, v26
	s_lshl_b32 s18, s18, 7
	s_nop 0
	v_addc_co_u32_e32 v7, vcc, 0, v27, vcc
	v_add_co_u32_e32 v10, vcc, 0x4000, v26
	s_ashr_i32 s19, s18, 31
	s_nop 0
	v_addc_co_u32_e32 v11, vcc, 0, v27, vcc
	v_add_co_u32_e32 v14, vcc, 0x6000, v26
	v_lshl_add_u64 v[42:43], s[18:19], 1, v[174:175]
	s_nop 0
	v_addc_co_u32_e32 v15, vcc, 0, v27, vcc
	v_add_co_u32_e32 v18, vcc, 0x8000, v26
	global_load_dwordx4 v[2:5], v[26:27], off
	s_nop 0
	global_load_dwordx4 v[6:9], v[6:7], off
	v_addc_co_u32_e32 v19, vcc, 0, v27, vcc
	v_add_co_u32_e32 v22, vcc, 0xa000, v26
	global_load_dwordx4 v[10:13], v[10:11], off
	s_nop 0
	global_load_dwordx4 v[14:17], v[14:15], off
	v_addc_co_u32_e32 v23, vcc, 0, v27, vcc
	v_add_co_u32_e32 v28, vcc, 0xc000, v26
	global_load_dwordx4 v[18:21], v[18:19], off
	s_nop 0
	global_load_dwordx4 v[22:25], v[22:23], off
	v_addc_co_u32_e32 v29, vcc, 0, v27, vcc
	v_add_co_u32_e32 v30, vcc, 0xe000, v26
	s_nop 1
	v_addc_co_u32_e32 v31, vcc, 0, v27, vcc
	v_add_co_u32_e32 v38, vcc, 0x100000, v42
	global_load_dwordx4 v[26:29], v[28:29], off
	s_nop 0
	global_load_dwordx4 v[30:33], v[30:31], off
	v_addc_co_u32_e32 v39, vcc, 0, v43, vcc
	v_add_co_u32_e32 v44, vcc, 0x200000, v42
	global_load_dwordx4 v[34:37], v[42:43], off
	s_nop 0
	global_load_dwordx4 v[38:41], v[38:39], off
	v_addc_co_u32_e32 v45, vcc, 0, v43, vcc
	v_add_co_u32_e32 v46, vcc, 0x300000, v42
	s_nop 1
	v_addc_co_u32_e32 v47, vcc, 0, v43, vcc
	global_load_dwordx4 v[42:45], v[44:45], off
	s_nop 0
	global_load_dwordx4 v[46:49], v[46:47], off
